# forgetting-attention loop role B: V staging store and next loads spread over its QK MFMA gaps (K store and decay-slot block stay ahead of the QK phase)
# baseline (speedup 1.0000x reference)
; __device__ __forceinline__ s16x4 vtr(ldsp p) { return __builtin_bit_cast(s16x4, __builtin_amdgcn_ds_read_tr16_b64_v4i16((LAS v4i16_t*)p)); }
; #define MASK_BLOCK() do { if (kt == 0 || kt >= diag0) { \
;             _Pragma("unroll") for (int r = 0; r < 16; ++r) { const int kpp = 64 * kt + crow(r, hi); \
;                 if (kpp < 48 || kpp > q_pp) s0[r] = -INFINITY; \
;                 if (kpp + 32 < 48 || kpp + 32 > q_pp) s1[r] = -INFINITY; } } } while (0)
; #define EXPSUM_BLOCK() do { psa = 0.f; psb = 0.f; \
;             _Pragma("unroll") for (int r = 0; r < 16; ++r) { s0[r] = __builtin_amdgcn_exp2f(s0[r]); s1[r] = __builtin_amdgcn_exp2f(s1[r]); psa += s0[r]; asm("" : "+v"(psa)); psb += s1[r]; asm("" : "+v"(psb)); } } while (0)
; template <bool DIFF>
; __device__ __forceinline__ void attn_unit(const AttnP& A, int b, int h, int qi, ldsp lds) {
;     ...
;             QK_BLOCK();
;             s16x4 vlo[8], vhi[8];
; #pragma unroll
;             for (int t = 0; t < 2; ++t)
; #pragma unroll
;                 for (int j = 0; j < 4; ++j) { vlo[t * 4 + j] = vtr(Vb + trb + (16 * j) * VP + t * 64); vhi[t * 4 + j] = vtr(Vb + trb + (16 * j + 8) * VP + t * 64); }
;             __builtin_amdgcn_sched_barrier(0);
;             MASK_BLOCK();
;             bool full = (kt == kt0);
;             float psa, psb;
;             if (!full) {
;                 EXPSUM_BLOCK();
;                 if (__any(psa + psb > 1.0e18f)) { full = true; QK_BLOCK();
.Lfb_s_top:
	s_bitcmp1_b32 s99, 0
	s_cselect_b32 s74, 0x5500, 0
	s_sub_i32 s75, 0x5500, s74
	v_exp_f32_e32 v106, v66
	v_exp_f32_e32 v124, v50
	v_exp_f32_e32 v107, v67
	v_exp_f32_e32 v125, v51
	v_add_f32_e32 v166, 0, v106
	v_add_f32_e32 v167, 0, v124
	v_exp_f32_e32 v108, v68
	v_exp_f32_e32 v126, v52
	v_add_f32_e32 v166, v107, v166
	v_add_f32_e32 v167, v125, v167
	v_exp_f32_e32 v109, v69
	v_exp_f32_e32 v127, v53
	v_add_f32_e32 v166, v108, v166
	v_add_f32_e32 v167, v126, v167
	v_exp_f32_e32 v110, v70
	v_exp_f32_e32 v128, v54
	v_add_f32_e32 v166, v109, v166
	v_add_f32_e32 v167, v127, v167
	v_exp_f32_e32 v111, v71
	v_exp_f32_e32 v129, v55
	v_add_f32_e32 v166, v110, v166
	v_add_f32_e32 v167, v128, v167
	v_exp_f32_e32 v112, v72
	v_exp_f32_e32 v130, v56
	v_add_f32_e32 v166, v111, v166
	v_add_f32_e32 v167, v129, v167
	v_exp_f32_e32 v113, v73
	v_exp_f32_e32 v131, v57
	v_add_f32_e32 v166, v112, v166
	v_add_f32_e32 v167, v130, v167
	v_exp_f32_e32 v116, v74
	v_exp_f32_e32 v132, v58
	v_add_f32_e32 v166, v113, v166
	v_add_f32_e32 v167, v131, v167
	v_exp_f32_e32 v117, v75
	v_exp_f32_e32 v133, v59
	v_add_f32_e32 v166, v116, v166
	v_add_f32_e32 v167, v132, v167
	v_exp_f32_e32 v118, v76
	v_exp_f32_e32 v134, v60
	v_add_f32_e32 v166, v117, v166
	v_add_f32_e32 v167, v133, v167
	v_exp_f32_e32 v119, v77
	v_exp_f32_e32 v135, v61
	v_add_f32_e32 v166, v118, v166
	v_add_f32_e32 v167, v134, v167
	v_exp_f32_e32 v120, v78
	v_exp_f32_e32 v136, v62
	v_add_f32_e32 v166, v119, v166
	v_add_f32_e32 v167, v135, v167
	v_exp_f32_e32 v121, v79
	v_exp_f32_e32 v137, v63
	v_add_f32_e32 v166, v120, v166
	v_add_f32_e32 v167, v136, v167
	v_exp_f32_e32 v122, v80
	v_exp_f32_e32 v138, v64
	v_add_f32_e32 v166, v121, v166
	v_add_f32_e32 v167, v137, v167
	v_exp_f32_e32 v123, v81
	v_exp_f32_e32 v139, v65
	v_add_f32_e32 v166, v122, v166
	v_add_f32_e32 v167, v138, v167
	s_nop 0
	v_add_f32_e32 v166, v123, v166
	v_add_f32_e32 v167, v139, v167
	v_add_f32_e32 v141, v166, v167
	v_cmp_lt_f32_e32 vcc, s85, v141
	s_cbranch_vccnz .Lfb_s_slow
; __device__ __forceinline__ unsigned cvtpk(float lo, float hi) { f32x2 v = {lo, hi}; bf16x2_t b = __builtin_convertvector(v, bf16x2_t); return __builtin_bit_cast(unsigned, b); }
; template <bool DIFF>
; __device__ __forceinline__ void attn_unit(const AttnP& A, int b, int h, int qi, ldsp lds) {
;     ...
;             bf16x8 pw[4];
; #pragma unroll
;             for (int j = 0; j < 4; ++j) {
;                 u32x4 pk;
;                 if (j < 2) { const int rb = 8 * (j & 1); pk.x = cvtpk(s0[rb], s0[rb + 1]); pk.y = cvtpk(s0[rb + 2], s0[rb + 3]); pk.z = cvtpk(s0[rb + 4], s0[rb + 5]); pk.w = cvtpk(s0[rb + 6], s0[rb + 7]); }
;                 else { const int rb = 8 * (j & 1); pk.x = cvtpk(s1[rb], s1[rb + 1]); pk.y = cvtpk(s1[rb + 2], s1[rb + 3]); pk.z = cvtpk(s1[rb + 4], s1[rb + 5]); pk.w = cvtpk(s1[rb + 6], s1[rb + 7]); }
;                 pw[j] = __builtin_bit_cast(bf16x8, pk);
;             }
;             __builtin_amdgcn_sched_barrier(0);
;             __builtin_amdgcn_s_setprio(1);
; #pragma unroll
;             for (int t = 0; t < 2; ++t)
; #pragma unroll
;                 for (int j = 0; j < 4; ++j) {
;                     const bf16x8 vf = (bf16x8){vlo[t * 4 + j][0], vlo[t * 4 + j][1], vlo[t * 4 + j][2], vlo[t * 4 + j][3], vhi[t * 4 + j][0], vhi[t * 4 + j][1], vhi[t * 4 + j][2], vhi[t * 4 + j][3]};
;                     o[t] = __builtin_amdgcn_mfma_f32_32x32x16_bf16(vf, pw[j], o[t], 0, 0, 0);
;                 }
;             if (DIFF) {
; #pragma unroll
;                 for (int t = 2; t < NTD; ++t)
; #pragma unroll
;                     for (int j = 0; j < 4; ++j) { vlo[(t - 2) * 4 + j] = vtr(Vb + trb + (16 * j) * VP + t * 64); vhi[(t - 2) * 4 + j] = vtr(Vb + trb + (16 * j + 8) * VP + t * 64); }
;                 __builtin_amdgcn_sched_barrier(0);
; #pragma unroll
;                 for (int t = 2; t < NTD; ++t)
; #pragma unroll
;                     for (int j = 0; j < 4; ++j) {
;                         const int i = (t - 2) * 4 + j;
;                         const bf16x8 vf = (bf16x8){vlo[i][0], vlo[i][1], vlo[i][2], vlo[i][3], vhi[i][0], vhi[i][1], vhi[i][2], vhi[i][3]};
;                         o[t] = __builtin_amdgcn_mfma_f32_32x32x16_bf16(vf, pw[j], o[t], 0, 0, 0);
;                     }
;             }
;             __builtin_amdgcn_s_setprio(0);
;         }
;         if (kt + 1 < nt) STORE_TILE((kt + 1) & 1);
;         __syncthreads();
;     }
	v_add_u32_e32 v169, s74, v150
	v_add_u32_e32 v0, s74, v164
	v_add_u32_e32 v168, s75, v161
	ds_read_b64_tr_b16 v[58:59], v168 offset:9216
	ds_read_b64_tr_b16 v[60:61], v168 offset:10752
	ds_read_b64_tr_b16 v[62:63], v168 offset:9280
	ds_read_b64_tr_b16 v[64:65], v168 offset:10816
	ds_read_b64_tr_b16 v[74:75], v168 offset:12288
	ds_read_b64_tr_b16 v[76:77], v168 offset:13824
	ds_read_b64_tr_b16 v[78:79], v168 offset:12352
	ds_read_b64_tr_b16 v[80:81], v168 offset:13888
	ds_read_b64_tr_b16 v[244:245], v168 offset:15360
	ds_read_b64_tr_b16 v[246:247], v168 offset:16896
	v_cvt_pk_bf16_f32 v66, v106, v107
	v_cvt_pk_bf16_f32 v67, v108, v109
	v_cvt_pk_bf16_f32 v68, v110, v111
	v_cvt_pk_bf16_f32 v69, v112, v113
	v_cvt_pk_bf16_f32 v70, v116, v117
	v_cvt_pk_bf16_f32 v71, v118, v119
	v_cvt_pk_bf16_f32 v72, v120, v121
	v_cvt_pk_bf16_f32 v73, v122, v123
	v_cvt_pk_bf16_f32 v50, v124, v125
	v_cvt_pk_bf16_f32 v51, v126, v127
	v_cvt_pk_bf16_f32 v52, v128, v129
	v_cvt_pk_bf16_f32 v53, v130, v131
	v_cvt_pk_bf16_f32 v54, v132, v133
	v_cvt_pk_bf16_f32 v55, v134, v135
	v_cvt_pk_bf16_f32 v56, v136, v137
	v_cvt_pk_bf16_f32 v57, v138, v139
	v_add_f32_e32 v154, v141, v154
	ds_read_b64_tr_b16 v[106:107], v168 offset:15424
	ds_read_b64_tr_b16 v[108:109], v168 offset:16960
	ds_read_b64_tr_b16 v[110:111], v168 offset:18432
	ds_read_b64_tr_b16 v[112:113], v168 offset:19968
	ds_read_b64_tr_b16 v[116:117], v168 offset:18496
	ds_read_b64_tr_b16 v[118:119], v168 offset:20032
	v_mov_b32_e32 v248, s97
	ds_read_b32 v248, v248
	ds_read_b128 v[120:123], v169
	ds_read_b128 v[124:127], v169 offset:4608
	ds_read_b128 v[128:131], v169 offset:32
	ds_read_b128 v[132:135], v169 offset:4640
	ds_read_b128 v[136:139], v169 offset:64
	ds_read_b128 v[170:173], v169 offset:4672
	s_setprio 1
	s_waitcnt lgkmcnt(15)
	v_mfma_f32_32x32x16_bf16 v[18:33], v[58:61], v[66:69], v[18:33]
	v_mfma_f32_32x32x16_bf16 v[2:17], v[62:65], v[66:69], v[2:17]
	v_mfma_f32_32x32x16_bf16 v[18:33], v[74:77], v[70:73], v[18:33]
	v_mfma_f32_32x32x16_bf16 v[2:17], v[78:81], v[70:73], v[2:17]
	s_waitcnt lgkmcnt(13)
	v_mfma_f32_32x32x16_bf16 v[18:33], v[244:247], v[50:53], v[18:33]
	ds_read_b128 v[244:247], v169 offset:96
	s_waitcnt lgkmcnt(12)
	v_mfma_f32_32x32x16_bf16 v[2:17], v[106:109], v[50:53], v[2:17]
	ds_read_b128 v[106:109], v169 offset:4704
	s_waitcnt lgkmcnt(11)
	v_mfma_f32_32x32x16_bf16 v[18:33], v[110:113], v[54:57], v[18:33]
	ds_read_b128 v[110:113], v0 offset:128
	s_waitcnt lgkmcnt(10)
	v_mfma_f32_32x32x16_bf16 v[2:17], v[116:119], v[54:57], v[2:17]
	ds_read_b128 v[116:119], v0 offset:4736
	s_waitcnt vmcnt(0)
	v_add_u32_e32 v115, s75, v156
	ds_write_b128 v115, v[98:101]
	s_and_saveexec_b64 s[0:1], s[44:45]
	v_xor_b32_e32 v0, 0x80000000, v155
	v_cvt_pk_bf16_f32 v0, v0, 0
	v_lshlrev_b32_e32 v249, 16, v0
	v_sub_f32_e64 v249, -v155, v249
	v_cvt_pk_bf16_f32 v162, v249, 0
	v_lshlrev_b32_e32 v162, 16, v162
	v_sub_f32_e32 v249, v249, v162
	v_cvt_pk_bf16_f32 v249, v249, 0
	v_and_or_b32 v112, v0, s83, v162
	v_and_or_b32 v113, v249, s83, 1.0
	v_mov_b32_e32 v115, v1
	v_add_u32_e32 v0, s75, v159
	ds_write_b128 v0, v[112:115] offset:128
	s_mov_b64 exec, s[0:1]
	s_waitcnt lgkmcnt(11)
	v_mfma_f32_32x32x16_bf16 v[66:81], v[120:123], v[90:93], v[34:49]
	v_add_u32_e32 v115, s74, v158
	ds_write_b128 v115, v[102:105] offset:9216
	s_waitcnt lgkmcnt(11)
	v_mfma_f32_32x32x16_bf16 v[50:65], v[124:127], v[90:93], v[34:49]
	v_sub_f32_e32 v249, v160, v248
	v_cvt_pk_bf16_f32 v162, v249, 0
	v_lshlrev_b32_e32 v162, 16, v162
	s_waitcnt lgkmcnt(10)
	v_mfma_f32_32x32x16_bf16 v[66:81], v[128:131], v[82:85], v[66:81]
	global_load_dwordx4 v[102:105], v[250:251], off
	v_lshl_add_u64 v[250:251], v[250:251], 0, s[26:27]
	global_load_dwordx4 v[98:101], v[152:153], off
	v_lshl_add_u64 v[152:153], v[152:153], 0, s[26:27]
	s_waitcnt lgkmcnt(9)
	v_mfma_f32_32x32x16_bf16 v[50:65], v[132:135], v[82:85], v[50:65]
	v_sub_f32_e32 v249, v249, v162
	v_cvt_pk_bf16_f32 v163, v249, 0
	v_and_b32_e32 v157, 0xffff, v163
	v_lshlrev_b32_e32 v163, 16, v163
	s_waitcnt lgkmcnt(8)
	v_mfma_f32_32x32x16_bf16 v[66:81], v[136:139], v[86:89], v[66:81]
	s_and_saveexec_b64 s[0:1], s[44:45]
	global_load_dword v155, v[252:253], off
	s_mov_b64 exec, s[0:1]
	s_mov_b64 s[0:1], 0x800
	v_lshl_add_u64 v[252:253], v[252:253], 0, s[0:1]
	s_waitcnt lgkmcnt(7)
	v_mfma_f32_32x32x16_bf16 v[50:65], v[170:173], v[86:89], v[50:65]
	v_sub_f32_e32 v249, v249, v163
	v_cvt_pk_bf16_f32 v249, v249, 0
	v_or_b32_e32 v162, 0x3f80, v162
	v_lshl_or_b32 v249, v249, 16, v157
	v_cndmask_b32_e64 v140, 0, v114, s[46:47]
	v_cndmask_b32_e64 v142, 0, v249, s[46:47]
	v_cndmask_b32_e64 v141, 0, v162, s[46:47]
	v_mov_b32_e32 v143, v1
	s_waitcnt lgkmcnt(6)
	v_mfma_f32_32x32x16_bf16 v[66:81], v[244:247], v[94:97], v[66:81]
	s_waitcnt lgkmcnt(5)
	v_mfma_f32_32x32x16_bf16 v[50:65], v[106:109], v[94:97], v[50:65]
	s_waitcnt lgkmcnt(4)
	v_mfma_f32_32x32x16_bf16 v[66:81], v[110:113], v[140:143], v[66:81]
	s_waitcnt lgkmcnt(3)
	v_mfma_f32_32x32x16_bf16 v[50:65], v[116:119], v[140:143], v[50:65]
	s_setprio 0
	s_waitcnt lgkmcnt(0)
	s_barrier
	s_add_i32 s99, s99, 1
	s_add_i32 s94, s94, 1
	s_add_i32 s97, s97, 4
	s_add_i32 s98, s98, 64
	s_add_i32 s0, s95, 0
	s_cmp_le_i32 s99, s0
	s_cbranch_scc1 .Lfb_s_top
